# unit-header tile decode simplified to ~11 SALU (gsz==8, nwg%8==0 folded) in in-GEMM and QKV unit loops, on top of peel
# speedup vs baseline: 1.0108x; 1.0108x over previous
.LBB0_181:
	s_add_i32 s59, s59, 1
	s_mul_i32 s4, s59, s21
	s_mul_hi_u32 s5, s59, s20
	s_add_i32 s5, s5, s4
	s_mul_i32 s4, s59, s20
	s_add_u32 s24, s4, s2
	s_addc_u32 s25, s5, s3
	v_cmp_gt_i64_e32 vcc, s[24:25], v[138:139]
	v_cmp_lt_i64_e64 s[4:5], s[24:25], v[136:137]
	s_cbranch_vccnz .LBB0_183
	s_lshr_b32 s10, s24, 3
	s_and_b32 s12, s24, 7
	s_lshl_b32 s12, s12, 1
	s_cmp_ge_u32 s10, 0xb0
	s_cbranch_scc0 .Ldec_0
	s_sub_u32 s10, s10, 0xb0
	s_add_u32 s12, s12, 1
.Ldec_0:
	s_lshl_b32 s12, s12, 3
	s_and_b32 s24, s10, 7
	s_or_b32 s12, s12, s24
	s_lshr_b32 s10, s10, 3

.LBB0_384:
	s_add_i32 s72, s72, 1
	s_mul_i32 s4, s72, s21
	s_mul_hi_u32 s5, s72, s20
	s_add_i32 s5, s5, s4
	s_mul_i32 s4, s72, s20
	s_add_u32 s52, s4, s2
	s_addc_u32 s53, s5, s3
	v_cmp_gt_i64_e32 vcc, s[52:53], v[144:145]
	v_cmp_lt_i64_e64 s[4:5], s[52:53], v[142:143]
	s_cbranch_vccnz .LBB0_386
	s_lshr_b32 s46, s52, 3
	s_and_b32 s48, s52, 7
	s_lshl_b32 s48, s48, 1
	s_cmp_ge_u32 s46, 0x60
	s_cbranch_scc0 .Ldec_2
	s_sub_u32 s46, s46, 0x60
	s_add_u32 s48, s48, 1
.Ldec_2:
	s_lshl_b32 s48, s48, 3
	s_and_b32 s52, s46, 7
	s_or_b32 s48, s48, s52
	s_lshr_b32 s46, s46, 3

.LBB0_721:
	s_add_i32 s63, s63, 1
	s_mul_i32 s10, s63, s21
	s_mul_hi_u32 s11, s63, s20
	s_add_i32 s11, s11, s10
	s_mul_i32 s10, s63, s20
	s_add_u32 s36, s10, s2
	s_addc_u32 s37, s11, s3
	v_cmp_gt_i64_e32 vcc, s[36:37], v[138:139]
	v_cmp_lt_i64_e64 s[10:11], s[36:37], v[136:137]
	s_cbranch_vccnz .LBB0_723
	s_lshr_b32 s18, s36, 3
	s_and_b32 s30, s36, 7
	s_lshl_b32 s30, s30, 1
	s_cmp_ge_u32 s18, 0xb0
	s_cbranch_scc0 .Ldec_4
	s_sub_u32 s18, s18, 0xb0
	s_add_u32 s30, s30, 1
.Ldec_4:
	s_lshl_b32 s30, s30, 3
	s_and_b32 s36, s18, 7
	s_or_b32 s30, s30, s36
	s_lshr_b32 s18, s18, 3

.LBB0_948:
	s_add_i32 s65, s65, 1
	s_mul_i32 s10, s65, s21
	s_mul_hi_u32 s11, s65, s20
	s_add_i32 s11, s11, s10
	s_mul_i32 s10, s65, s20
	s_add_u32 s44, s10, s2
	s_addc_u32 s45, s11, s3
	v_cmp_gt_i64_e32 vcc, s[44:45], v[138:139]
	v_cmp_lt_i64_e64 s[10:11], s[44:45], v[136:137]
	s_cbranch_vccnz .LBB0_950
	s_lshr_b32 s18, s44, 3
	s_and_b32 s36, s44, 7
	s_lshl_b32 s36, s36, 1
	s_cmp_ge_u32 s18, 0xb0
	s_cbranch_scc0 .Ldec_7
	s_sub_u32 s18, s18, 0xb0
	s_add_u32 s36, s36, 1
.Ldec_7:
	s_lshl_b32 s36, s36, 3
	s_and_b32 s44, s18, 7
	s_or_b32 s36, s36, s44
	s_lshr_b32 s18, s18, 3

.LBB0_1431:
	s_add_i32 s59, s59, 1
	s_mul_i32 s8, s59, s21
	s_mul_hi_u32 s9, s59, s20
	s_add_i32 s9, s9, s8
	s_mul_i32 s8, s59, s20
	s_add_u32 s30, s8, s2
	s_addc_u32 s31, s9, s3
	v_cmp_gt_i64_e32 vcc, s[30:31], v[138:139]
	v_cmp_lt_i64_e64 s[8:9], s[30:31], v[136:137]
	s_cbranch_vccnz .LBB0_1433
	s_lshr_b32 s16, s30, 3
	s_and_b32 s18, s30, 7
	s_lshl_b32 s18, s18, 1
	s_cmp_ge_u32 s16, 0xb0
	s_cbranch_scc0 .Ldec_11
	s_sub_u32 s16, s16, 0xb0
	s_add_u32 s18, s18, 1
.Ldec_11:
	s_lshl_b32 s18, s18, 3
	s_and_b32 s30, s16, 7
	s_or_b32 s18, s18, s30
	s_lshr_b32 s16, s16, 3
